# v22 + static s_setprio 1 for waves 4-7 in attention and both scan passes + grid-barrier L1 invalidate issued before the spin
# baseline (speedup 1.0000x reference)
; __device__ __forceinline__ unsigned xb_ld(unsigned* p)              { return __hip_atomic_load(p, __ATOMIC_RELAXED, __HIP_MEMORY_SCOPE_AGENT); }
; __device__ __forceinline__ unsigned xb_add(unsigned* p, unsigned v) { return __hip_atomic_fetch_add(p, v, __ATOMIC_RELAXED, __HIP_MEMORY_SCOPE_AGENT); }
; #define XB_SPIN(cond, bar) do { unsigned _sp = 0; while (cond) { __builtin_amdgcn_s_sleep(1); \
;     if ((++_sp & 255u) == 0u) { if (xb_ld(&(bar)[XB_TMO])) break; if (_sp > XB_SPIN_CAP) { atomicAdd(&(bar)[XB_TMO], 1u); break; } } } } while (0)
; __device__ __forceinline__ void xcd_barrier(const XcdBarrier& b) {
;     ...
;             __builtin_amdgcn_fence(__ATOMIC_RELEASE, "agent");
;             asm volatile("s_waitcnt vmcnt(0)" ::: "memory");
;             const unsigned og = xb_add(&bar[XB_TOP], 1u);
;             const unsigned tg = og / nx;
;             if (og + 1u == (tg + 1u) * nx) xb_add(&bar[XB_TOPGEN], 1u);
;             else XB_SPIN(xb_ld(&bar[XB_TOPGEN]) == tg, bar);
;             __builtin_amdgcn_fence(__ATOMIC_ACQUIRE, "agent");
;             xb_add(&bar[XB_XGEN(b.x)], 1u);
;             asm volatile("s_waitcnt vmcnt(0)" ::: "memory");
.LBB0_56:
	s_or_b64 exec, exec, s[4:5]
	v_mov_b32_e32 v0, s26
	v_add_co_u32_e32 v2, vcc, 0x2000, v0
	v_mov_b32_e32 v0, s2
	s_nop 0
	v_addc_co_u32_e32 v3, vcc, 0, v0, vcc
	s_waitcnt vmcnt(0) lgkmcnt(0)
	flat_atomic_add v[2:3], v194 offset:1024
	s_waitcnt vmcnt(0)

; __global__ void __launch_bounds__(NTHR, 2) fwd_megakernel(Args a) {
;     ...
;             for (int part = 0; part < 2; ++part) {
;                 const bool do_attn = (part == 0) == (first_attn != 0);
;                 unsigned char* wsl = ws; asm volatile("" : "+s"(wsl));
;                 bf16* XB = (bf16*)(wsl + WS_XB); bf16* OB = (bf16*)(wsl + WS_OB); bf16* BIG = (bf16*)(wsl + WS_BIG);
;                 if (!do_attn) {
;                     float* ssq = (float*)(wsl + WS_SSQ);
;                     bf16* Win_t = (bf16*)(wsl + WS_WIN); bf16* Wout_t = (bf16*)(wsl + WS_WOUT); bf16* Wqkv_t = (bf16*)(wsl + WS_WQKV); bf16* Waout_t = (bf16*)(wsl + WS_WAOUT);
;                     bf16* W1_t = (bf16*)(wsl + WS_W1); bf16* W2_t = (bf16*)(wsl + WS_W2);
;                     int gk = -1; const bf16* A = XB; const bf16* Bt = nullptr; int N = 0, K = D, gg = 0;
;                     if (s < n1) {
;                         if (!odd) { if (s == 0) { gk = 0; Bt = Win_t + (size_t)j * 4 * D * D; N = 4 * D; } }
;                         else if (s < 3) { gk = 0; gg = s; Bt = Wqkv_t + (size_t)j * 9 * D * D + (size_t)s * 3 * D * D; N = 3 * D; }
;                     } else if (s == n1) { gk = 2; A = OB; Bt = (odd ? Waout_t : Wout_t) + (size_t)j * D * D; N = D; }
;                     else if (s == n1 + 1) { gk = 1; Bt = W1_t + (size_t)layer * FF * D; N = FF; }
;                     else { gk = 2; A = BIG; Bt = W2_t + (size_t)layer * D * FF; N = D; K = FF; }
;                     if (gk >= 0) {
;                         bf16* dq = (bf16*)xres;
;                         const bool spl = odd && gk == 0; const bool bufB = spl && gg == 1;
;                         bf16* Oq = bufB ? dq : BIG; bf16* Ok = bufB ? dq + (size_t)M * D : BIG + (size_t)M * D; bf16* Ov = bufB ? BIG + (size_t)3 * M * D : BIG + (size_t)2 * M * D;
;                         pg8::Gemm gm{A, Bt, M, N, K}; pg8::StaticOrder S; S.init(M, N, G, (int)blockIdx.x);
;                         pg8::EpiAny E{gk, Oq, spl ? D : N, ssq, XB, ssq, Ok, Ov, spl ? 1 : 0};
;                         pg8::gemm_phase<pg8::EpiAny, pg8::StaticOrder, true, true>(lds, gm, S, E);
;                         __syncthreads();
;                     }
;                 } else if (s < n1) {
;                     if (!odd) {
.LBB0_60:
	v_readlane_b32 s4, v251, 0
	v_readlane_b32 s6, v251, 2
	v_readlane_b32 s7, v251, 3
	s_mov_b64 s[34:35], s[6:7]
	s_add_u32 s18, s34, 0xc000000
	s_addc_u32 s19, s35, 0
	s_add_u32 s82, s34, 0x10000000
	s_addc_u32 s83, s35, 0
	s_cmp_lg_u32 s0, s79
	s_mov_b64 s[12:13], 0
	s_mov_b64 s[0:1], -1
	v_readlane_b32 s5, v251, 1
	s_cbranch_scc0 .LBB0_188
	v_readlane_b32 s4, v250, 54
	v_readlane_b32 s5, v250, 55
	s_mov_b64 s[0:1], 0
	s_and_b64 vcc, exec, s[4:5]
	s_cbranch_vccz .LBB0_188
	v_readlane_b32 s4, v250, 22
	v_readlane_b32 s5, v250, 23
	s_and_b64 vcc, exec, s[4:5]
	s_cbranch_vccz .LBB0_96
	s_cmp_lt_i32 s36, 2
	s_cbranch_scc1 .LBB0_97
	s_mov_b64 s[42:43], 0
	s_cmp_eq_u32 s36, 2
	s_cbranch_scc0 .LBB0_99
	v_readlane_b32 s4, v251, 31
	v_mov_b32_e32 v135, v163
	v_readlane_b32 s5, v251, 32
	v_writelane_b32 v249, s62, 2
	s_andn2_b64 vcc, exec, s[4:5]
	v_readfirstlane_b32 s2, v135
	v_writelane_b32 v249, s63, 3
	s_cmpk_lt_u32 s2, 0x100
	s_cbranch_scc1 .Lmy_scan2_noprio
	s_setprio 1
.Lmy_scan2_noprio:
	s_cbranch_vccnz .LBB0_98
	v_lshlrev_b32_e32 v0, 3, v135
	v_and_b32_e32 v2, 0x78, v0
	v_readlane_b32 s8, v250, 31
	s_ashr_i32 s26, s2, 7
	s_ashr_i32 s12, s2, 8
	s_ashr_i32 s4, s2, 6
	v_lshlrev_b32_e32 v0, 2, v2
	v_readlane_b32 s9, v250, 32
	s_and_b32 s10, s2, 0x3fffff80
	s_and_b32 s13, s4, 3
	s_lshl_b32 s4, s4, 11
	s_lshl_b32 s6, s12, 11
	v_lshl_add_u64 v[136:137], s[8:9], 0, v[0:1]
	s_lshl_b32 s8, s26, 3
	s_lshl_b32 s10, s10, 2
	s_ashr_i32 s5, s4, 31
	s_ashr_i32 s7, s6, 31
	s_ashr_i32 s9, s8, 31
	s_add_i32 s10, s10, 0
	s_cmpk_lt_u32 s2, 0x80
	s_cselect_b64 s[44:45], -1, 0
	s_cmpk_gt_u32 s2, 0x7f
	s_cselect_b64 s[46:47], -1, 0
	s_cmp_lg_u32 s26, 1
	s_cselect_b64 s[48:49], -1, 0
	s_cmp_eq_u32 s26, 2
	s_cselect_b64 s[50:51], -1, 0
	s_lshl_b32 s2, s13, 6
	s_lshl_b32 s14, s12, 7
	s_lshl_b32 s15, s12, 6
	s_mulk_i32 s12, 0x4200
	s_add_i32 s11, s2, 0
	s_add_i32 s20, s12, 0
	s_lshl_b32 s2, s13, 7
	s_add_i32 s20, s20, s2
	s_add_i32 s21, s14, 0
	s_lshl_b64 s[6:7], s[6:7], 2
	v_readlane_b32 s2, v251, 33
	s_add_u32 s6, s2, s6
	v_readlane_b32 s2, v251, 34
	s_addc_u32 s7, s2, s7
	s_lshl_b64 s[4:5], s[4:5], 2
	v_readlane_b32 s36, v251, 0
	v_and_b32_e32 v3, 63, v135
	v_readlane_b32 s37, v251, 1
	s_add_u32 s4, s36, s4
	v_and_b32_e32 v134, 0x7f, v135
	v_ashrrev_i32_e32 v138, 4, v135
	v_lshlrev_b32_e32 v0, 2, v3
	s_addc_u32 s5, s37, s5
	v_ashrrev_i32_e32 v139, 31, v138
	s_mulk_i32 s26, 0x880
	v_lshl_add_u64 v[140:141], s[6:7], 0, v[0:1]
	v_lshl_add_u64 v[142:143], s[4:5], 0, v[0:1]
	v_lshlrev_b32_e32 v144, 1, v134
	v_lshlrev_b32_e32 v146, 1, v2
	s_mov_b32 s27, s78
	s_mov_b32 s36, s78
	v_readlane_b32 s38, v251, 2
	v_readlane_b32 s39, v251, 3
	s_branch .LBB0_68

; #define GAS __attribute__((address_space(1)))
; template <int pass> __device__ __forceinline__ void scan_phase(LAS unsigned char* lds, const bf16* P  , bf16* OB, float* scr, const float* lb0, const float* lb1, int jl, const float* onorm, int u_lo, int u_hi) {
;     int tid = threadIdx.x; asm volatile("" : "+v"(tid));
;     const int wave = __builtin_amdgcn_readfirstlane(tid >> 6), wj = wave & 3, kh = wave >> 2, quarter = wave >> 1;
;     LAS unsigned char* Qi = lds; LAS unsigned char* Ki = lds + SC_IMG; LAS unsigned char* Vi = lds + 2 * SC_IMG;
;     LAS float* totq = (LAS float*)(lds + 3 * SC_IMG); LAS float* eR = totq + 512; LAS float* eT1 = eR + 128; LAS float* Ot = eT1 + 128;
;     float* Tg = scr; float* Dg = scr + (size_t)512 * 16384;
;     for (int u = u_lo + blockIdx.x; u < u_hi; u += gridDim.x) {
;         const int sc = u & 7, h = (u >> 3) & 7, b = u >> 6;
;         const size_t tok0 = (size_t)b * SEQ + sc * 512;
;         f32x16 S[2];
; #pragma unroll
;         for (int i = 0; i < 16; ++i) { S[0][i] = 0.f; S[1][i] = 0.f; }
;         if (pass == 2) {
;             for (int p = 0; p < sc; ++p) { const GAS float* Tp = (const GAS float*)Tg + (size_t)(u - sc + p) * 16384 + wave * 2048 + (tid & 63); const GAS float* Dp = (const GAS float*)Dg + (size_t)(u - sc + p) * 4096 + kh * 2048 + (tid & 63);
;                 asm volatile("" : "+v"(Tp), "+v"(Dp));
; #pragma unroll
;                 for (int j2 = 0; j2 < 2; ++j2)
; #pragma unroll
;                     for (int i = 0; i < 16; ++i) S[j2][i] = Dp[(j2 * 16 + i) * 64] * S[j2][i] + Tp[(j2 * 16 + i) * 64]; }
;         }
;         float gsum = 1.f;
;         float lb = 0.f; if (jl) lb = sigmoidf_(((const GAS float*)lb1)[h * 128 + (tid & 127)] - ((const GAS float*)lb0)[h * 128 + (tid & 127)]);
;         f32x4 n0 = (f32x4){0.f, 0.f, 0.f, 0.f}, n1 = n0;
;         if (pass == 2) { const GAS float* on = (const GAS float*)onorm + h * 128 + 8 * (tid & 15); n0 = *(const f32x4*)on; n1 = *(const GAS f32x4*)(on + 4); }
; __global__ void __launch_bounds__(NTHR, 2) fwd_megakernel(Args a) {
;     ...
;                         if (s == 1) { scan_phase<1>(lds, BIG, OB, xres  , a.hgrn_lb, a.hgrn_lb + D, j, a.hgrn_out_norm + j * D, 0, 512); __syncthreads(); }
;                         else if (s == 2) { scan_phase<2>(lds, BIG, OB, xres, a.hgrn_lb, a.hgrn_lb + D, j, a.hgrn_out_norm + j * D, 0, 512); __syncthreads(); }
.LBB0_98:
	v_readlane_b32 s62, v249, 2
	s_setprio 0
	s_barrier
	s_mov_b64 s[12:13], -1
	v_readlane_b32 s63, v249, 3
.LBB0_99:
	v_readlane_b32 s36, v249, 1
	s_and_b64 vcc, exec, s[42:43]
	s_cbranch_vccz .LBB0_134
	s_cmp_eq_u32 s36, 1
	s_cbranch_scc0 .LBB0_134
	v_readlane_b32 s4, v251, 31
	s_waitcnt vmcnt(0)
	v_mov_b32_e32 v103, v163
	v_readlane_b32 s5, v251, 32
	s_andn2_b64 vcc, exec, s[4:5]
	v_readfirstlane_b32 s11, v103
	s_cmpk_lt_u32 s11, 0x100
	s_cbranch_scc1 .Lmy_scan1_noprio
	s_setprio 1
.Lmy_scan1_noprio:
	s_cbranch_vccnz .LBB0_133
	s_ashr_i32 s26, s11, 7
	s_and_b32 s4, s11, 0x3fffff80
	s_ashr_i32 s14, s11, 6
	s_lshl_b32 s2, s26, 3
	s_lshl_b32 s4, s4, 2
	s_ashr_i32 s27, s11, 8
	s_and_b32 s36, s14, 3
	s_ashr_i32 s6, s2, 31
	s_add_i32 s7, s4, 0
	s_cmpk_lt_u32 s11, 0x80
	s_cselect_b64 s[4:5], -1, 0
	s_cmpk_gt_u32 s11, 0x7f
	s_cselect_b64 s[12:13], -1, 0
	s_cmp_lg_u32 s26, 1
	s_cselect_b64 s[16:17], -1, 0
	s_cmp_eq_u32 s26, 2
	s_cselect_b64 s[20:21], -1, 0
	s_lshl_b32 s14, s14, 11
	s_lshl_b32 s8, s36, 6
	s_lshl_b32 s9, s27, 7
	s_ashr_i32 s15, s14, 31
	s_add_i32 s8, s8, 0
	s_add_i32 s9, s9, 0
	s_lshl_b32 s10, s27, 6
	s_lshl_b64 s[14:15], s[14:15], 2
	v_readlane_b32 s40, v251, 0
	v_lshlrev_b32_e32 v0, 3, v103
	v_readlane_b32 s41, v251, 1
	s_add_u32 s14, s40, s14
	v_and_b32_e32 v2, 0x78, v0
	s_addc_u32 s15, s41, s15
	v_and_b32_e32 v0, 63, v103
	v_lshlrev_b32_e32 v0, 2, v0
	s_cmp_eq_u32 s36, 0
	v_lshl_add_u64 v[106:107], s[14:15], 0, v[0:1]
	s_cselect_b64 s[40:41], -1, 0
	s_lshl_b32 s14, s27, 11
	s_ashr_i32 s15, s14, 31
	s_lshl_b64 s[14:15], s[14:15], 2
	v_readlane_b32 s23, v251, 33
	s_add_u32 s14, s23, s14
	v_readlane_b32 s23, v251, 34
	s_addc_u32 s15, s23, s15
	v_lshl_add_u64 v[108:109], s[14:15], 0, v[0:1]
	s_and_b32 s11, s11, 0xffffff00
	v_lshrrev_b32_e32 v0, 1, v103
	v_and_b32_e32 v102, 0x7f, v103
	v_ashrrev_i32_e32 v104, 4, v103
	v_readlane_b32 s42, v251, 2
	s_add_i32 s11, s11, 0
	v_and_b32_e32 v0, 16, v0
	v_ashrrev_i32_e32 v105, 31, v104
	v_lshl_add_u32 v150, v102, 2, 0
	v_add_u32_e32 v151, s11, v0
	s_mul_i32 s11, s26, 0x880
	v_lshlrev_b32_e32 v110, 1, v102
	v_lshlrev_b32_e32 v112, 1, v2
	v_readlane_b32 s14, v250, 11
	s_mov_b32 s42, s78
	v_readlane_b32 s43, v251, 3
	s_branch .LBB0_105

; __global__ void __launch_bounds__(NTHR, 2) fwd_megakernel(Args a) {
;     ...
;                         if (s == 1) { scan_phase<1>(lds, BIG, OB, xres  , a.hgrn_lb, a.hgrn_lb + D, j, a.hgrn_out_norm + j * D, 0, 512); __syncthreads(); }
.LBB0_133:
	s_mov_b64 s[12:13], -1
	v_readlane_b32 s36, v249, 1
	s_setprio 0
	s_barrier

; __device__ __forceinline__ void attn_phase(LAS unsigned char* lds, const bf16* Qg, const bf16* Kg, const bf16* Vg  , bf16* OB, float* LSE, int g, int dsh, int u_lo, int u_hi) {
;     ...
;     if (u_lo + (int)blockIdx.x < u_hi) { ATTN_DECODE(u_lo + (int)blockIdx.x, h0, Q00, tb0) ATTN_FETCH(h0, Q00, tb0); }
; __global__ void __launch_bounds__(NTHR, 2) fwd_megakernel(Args a) {
;     ...
;                     } else if (s > 0) {
;                         const int ag = s - 1; const bool bufB = ag == 1; bf16* dq = (bf16*)xres;
;                         const bf16* Qg = bufB ? dq : BIG; const bf16* Kg = bufB ? dq + (size_t)M * D : BIG + (size_t)M * D; const bf16* Vg = bufB ? BIG + (size_t)3 * M * D : BIG + (size_t)2 * M * D;
;                         float* lse = (float*)(wsl + WS_WIN);
;                         attn_phase(lds, Qg, Kg, Vg, OB, lse, ag, 2 * ag, 0, 2048);
.LBB0_135:
	v_readlane_b32 s4, v250, 48
	v_readlane_b32 s5, v250, 49
	s_and_b64 vcc, exec, s[4:5]
	s_cbranch_vccz .LBB0_188
	s_add_u32 s2, s34, 0x14000000
	v_readlane_b32 s4, v250, 56
	s_addc_u32 s6, s35, 0
	v_readlane_b32 s5, v250, 57
	s_and_b64 s[4:5], s[4:5], exec
	v_readlane_b32 s4, v251, 29
	s_cselect_b32 s8, s4, s6
	v_readlane_b32 s4, v251, 28
	s_cselect_b32 s9, s4, s2
	v_readlane_b32 s4, v251, 35
	v_readlane_b32 s2, v250, 58
	v_readlane_b32 s5, v251, 36
	s_add_u32 s10, s34, s2
	v_mov_b32_e32 v166, v163
	v_cndmask_b32_e64 v0, 0, 1, s[4:5]
	v_writelane_b32 v249, s62, 2
	s_addc_u32 s11, s35, 0
	v_cmp_ne_u32_e64 s[38:39], 1, v0
	s_andn2_b64 vcc, exec, s[4:5]
	v_readfirstlane_b32 s2, v166
	s_cmpk_lt_u32 s2, 0x100
	s_cbranch_scc1 .Lmy_attn_noprio
	s_setprio 1
.Lmy_attn_noprio:
	v_writelane_b32 v249, s63, 3
	s_cbranch_vccnz .LBB0_138
	v_readlane_b32 s100, v250, 60
	s_and_b32 s101, s100, 0xfff
	s_lshl_b32 s101, s101, 12
	s_lshr_b32 s101, s101, s30
	s_andn2_b32 s100, s100, 0xfff
	s_lshl_b32 s100, s100, 4
	s_add_i32 s100, s100, s101
	s_and_b32 s101, s78, 15
	s_lshl_b32 s101, s101, 12
	s_add_i32 s100, s100, s101
	s_mov_b32 s101, 0
	s_movk_i32 s4, 0xbff
	v_cmp_lt_i32_e32 vcc, s4, v166
	v_readlane_b32 s5, v250, 62
	v_readlane_b32 s12, v250, 60
	v_cndmask_b32_e32 v0, 0, v196, vcc
	v_add_u32_e32 v0, v0, v166
	v_ashrrev_i32_e32 v0, 3, v0
	v_add_u32_e32 v0, s5, v0
	v_max_i32_e32 v0, 0, v0
	v_lshlrev_b64 v[4:5], 0, v[0:1]
	v_readlane_b32 s13, v250, 61
	v_mov_b32_e32 v6, s8
	v_mov_b32_e32 v7, s11
	v_mov_b32_e32 v8, s9
	v_mov_b32_e32 v9, s10
	v_lshl_add_u64 v[4:5], v[4:5], 0, s[100:101]
	v_readlane_b32 s6, v250, 13
	v_cndmask_b32_e32 v3, v6, v7, vcc
	v_cndmask_b32_e32 v2, v8, v9, vcc
	v_lshlrev_b64 v[4:5], 7, v[4:5]
	v_readlane_b32 s7, v250, 14
	v_lshl_add_u64 v[2:3], v[2:3], 0, v[4:5]
	s_mov_b32 s7, s95
	v_lshlrev_b32_e32 v0, 4, v166
	v_lshl_add_u64 v[2:3], v[2:3], 0, 0
	v_and_b32_e32 v0, 0x70, v0
	s_movk_i32 s4, 0x9ff
	v_lshl_add_u64 v[2:3], v[2:3], 0, v[0:1]
	v_cmp_lt_i32_e32 vcc, s4, v166
	global_load_dwordx4 v[82:85], v[2:3], off
	v_mov_b32_e32 v3, v1
	v_cndmask_b32_e32 v2, 0, v196, vcc
	v_add3_u32 v2, v166, v2, s64
	v_ashrrev_i32_e32 v2, 3, v2
	v_add_u32_e32 v2, s5, v2
	v_max_i32_e32 v2, 0, v2
	v_lshlrev_b64 v[2:3], 0, v[2:3]
	v_lshl_add_u64 v[2:3], v[2:3], 0, s[100:101]
	v_cndmask_b32_e32 v5, v6, v7, vcc
	v_cndmask_b32_e32 v4, v8, v9, vcc
	v_lshlrev_b64 v[2:3], 7, v[2:3]
	v_lshl_add_u64 v[2:3], v[4:5], 0, v[2:3]
	v_lshl_add_u64 v[2:3], v[2:3], 0, 0
	s_movk_i32 s4, 0x7ff
	v_lshl_add_u64 v[2:3], v[2:3], 0, v[0:1]
	v_cmp_lt_i32_e32 vcc, s4, v166
	global_load_dwordx4 v[86:89], v[2:3], off
	s_movk_i32 s4, 0x400
	v_cndmask_b32_e32 v2, 0, v196, vcc
	v_add3_u32 v2, v166, v2, s4
	v_ashrrev_i32_e32 v2, 3, v2
	v_add_u32_e32 v2, s5, v2
	v_max_i32_e32 v2, 0, v2
	v_mov_b32_e32 v3, v1
	v_lshlrev_b64 v[2:3], 0, v[2:3]
	v_lshl_add_u64 v[2:3], v[2:3], 0, s[100:101]
	v_cndmask_b32_e32 v5, v6, v7, vcc
	v_cndmask_b32_e32 v4, v8, v9, vcc
	v_lshlrev_b64 v[2:3], 7, v[2:3]
	v_lshl_add_u64 v[2:3], v[4:5], 0, v[2:3]
	v_lshl_add_u64 v[2:3], v[2:3], 0, 0
	s_movk_i32 s4, 0x5ff
	v_lshl_add_u64 v[2:3], v[2:3], 0, v[0:1]
	v_cmp_lt_i32_e32 vcc, s4, v166
	global_load_dwordx4 v[90:93], v[2:3], off
	s_movk_i32 s4, 0x600
	v_cndmask_b32_e32 v2, 0, v196, vcc
	v_add3_u32 v2, v166, v2, s4
	v_ashrrev_i32_e32 v2, 3, v2
	v_add_u32_e32 v2, s5, v2
	v_max_i32_e32 v2, 0, v2
	v_mov_b32_e32 v3, v1
	v_lshlrev_b64 v[2:3], 0, v[2:3]
	v_lshl_add_u64 v[2:3], v[2:3], 0, s[100:101]
	v_cndmask_b32_e32 v5, v6, v7, vcc
	v_cndmask_b32_e32 v4, v8, v9, vcc
	v_lshlrev_b64 v[2:3], 7, v[2:3]
	v_lshl_add_u64 v[2:3], v[4:5], 0, v[2:3]
	v_lshl_add_u64 v[2:3], v[2:3], 0, 0
	s_movk_i32 s4, 0x3ff
	v_lshl_add_u64 v[2:3], v[2:3], 0, v[0:1]
	v_cmp_lt_i32_e32 vcc, s4, v166
	global_load_dwordx4 v[94:97], v[2:3], off
	s_movk_i32 s4, 0x800
	v_cndmask_b32_e32 v2, 0, v196, vcc
	v_add3_u32 v2, v166, v2, s4
	v_ashrrev_i32_e32 v2, 3, v2
	v_add_u32_e32 v2, s5, v2
	v_max_i32_e32 v2, 0, v2
	v_mov_b32_e32 v3, v1
	v_lshlrev_b64 v[2:3], 0, v[2:3]
	v_lshl_add_u64 v[2:3], v[2:3], 0, s[100:101]
	v_cndmask_b32_e32 v5, v6, v7, vcc
	v_cndmask_b32_e32 v4, v8, v9, vcc
	v_lshlrev_b64 v[2:3], 7, v[2:3]
	v_lshl_add_u64 v[2:3], v[4:5], 0, v[2:3]
	v_lshl_add_u64 v[2:3], v[2:3], 0, 0
; __device__ __forceinline__ void attn_phase(LAS unsigned char* lds, const bf16* Qg, const bf16* Kg, const bf16* Vg  , bf16* OB, float* LSE, int g, int dsh, int u_lo, int u_hi) {
;     ...
;     if (u_lo + (int)blockIdx.x < u_hi) { ATTN_DECODE(u_lo + (int)blockIdx.x, h0, Q00, tb0) ATTN_FETCH(h0, Q00, tb0); }
	s_movk_i32 s4, 0x1ff
	v_lshl_add_u64 v[2:3], v[2:3], 0, v[0:1]
	v_cmp_lt_i32_e32 vcc, s4, v166
	global_load_dwordx4 v[98:101], v[2:3], off
	s_movk_i32 s4, 0xa00
	v_cndmask_b32_e32 v2, 0, v196, vcc
	v_add3_u32 v2, v166, v2, s4
	v_ashrrev_i32_e32 v2, 3, v2
	v_add_u32_e32 v2, s5, v2
	v_max_i32_e32 v2, 0, v2
	v_mov_b32_e32 v3, v1
	v_lshlrev_b64 v[2:3], 0, v[2:3]
	v_lshl_add_u64 v[2:3], v[2:3], 0, s[100:101]
	v_cndmask_b32_e32 v5, v6, v7, vcc
	v_cndmask_b32_e32 v4, v8, v9, vcc
	v_lshlrev_b64 v[2:3], 7, v[2:3]
	v_lshl_add_u64 v[2:3], v[4:5], 0, v[2:3]
	v_lshl_add_u64 v[2:3], v[2:3], 0, 0
	v_lshl_add_u64 v[2:3], v[2:3], 0, v[0:1]
	global_load_dwordx4 v[102:105], v[2:3], off
	v_add_u32_e32 v2, 0xc00, v166
	v_cmp_lt_i32_e32 vcc, -1, v166
	v_mov_b32_e32 v3, v1
	s_movk_i32 s4, 0xfdff
	v_cndmask_b32_e32 v2, v2, v166, vcc
	v_ashrrev_i32_e32 v2, 3, v2
	v_add_u32_e32 v2, s5, v2
	v_max_i32_e32 v2, 0, v2
	v_lshlrev_b64 v[2:3], 0, v[2:3]
	v_lshl_add_u64 v[2:3], v[2:3], 0, s[100:101]
	v_cndmask_b32_e32 v5, v6, v7, vcc
	v_cndmask_b32_e32 v4, v8, v9, vcc
	v_lshlrev_b64 v[2:3], 7, v[2:3]
	v_lshl_add_u64 v[2:3], v[4:5], 0, v[2:3]
	v_lshl_add_u64 v[2:3], v[2:3], 0, 0
	v_lshl_add_u64 v[2:3], v[2:3], 0, v[0:1]
	v_cmp_lt_i32_e32 vcc, s4, v166
	global_load_dwordx4 v[106:109], v[2:3], off
	s_movk_i32 s4, 0xe00
	v_cndmask_b32_e32 v2, 0, v196, vcc
	v_add3_u32 v2, v166, v2, s4
	v_ashrrev_i32_e32 v2, 3, v2
	v_add_u32_e32 v2, s5, v2
	v_max_i32_e32 v2, 0, v2
	v_mov_b32_e32 v3, v1
	v_lshlrev_b64 v[2:3], 0, v[2:3]
	v_lshl_add_u64 v[2:3], v[2:3], 0, s[100:101]
	v_cndmask_b32_e32 v5, v6, v7, vcc
	v_cndmask_b32_e32 v4, v8, v9, vcc
	v_lshlrev_b64 v[2:3], 7, v[2:3]
	v_lshl_add_u64 v[2:3], v[4:5], 0, v[2:3]
	v_lshl_add_u64 v[2:3], v[2:3], 0, 0
	s_movk_i32 s4, 0xfbff
	v_lshl_add_u64 v[2:3], v[2:3], 0, v[0:1]
	v_cmp_lt_i32_e32 vcc, s4, v166
	global_load_dwordx4 v[110:113], v[2:3], off
	v_mov_b32_e32 v3, v1
	v_cndmask_b32_e32 v2, 0, v196, vcc
	v_add3_u32 v2, v166, v2, s72
	v_ashrrev_i32_e32 v2, 3, v2
	v_add_u32_e32 v2, s5, v2
	v_max_i32_e32 v2, 0, v2
	v_lshlrev_b64 v[2:3], 0, v[2:3]
	v_lshl_add_u64 v[2:3], v[2:3], 0, s[100:101]
	v_cndmask_b32_e32 v5, v6, v7, vcc
	v_cndmask_b32_e32 v4, v8, v9, vcc
	v_lshlrev_b64 v[2:3], 7, v[2:3]
	v_lshl_add_u64 v[2:3], v[4:5], 0, v[2:3]
	v_lshl_add_u64 v[2:3], v[2:3], 0, 0
	s_movk_i32 s4, 0xf9ff
	v_lshl_add_u64 v[2:3], v[2:3], 0, v[0:1]
	v_cmp_lt_i32_e32 vcc, s4, v166
	global_load_dwordx4 v[114:117], v[2:3], off
	s_movk_i32 s4, 0x1200
	v_cndmask_b32_e32 v2, 0, v196, vcc
	v_add3_u32 v2, v166, v2, s4
	v_ashrrev_i32_e32 v2, 3, v2
	v_add_u32_e32 v2, s5, v2
	v_max_i32_e32 v2, 0, v2
	v_mov_b32_e32 v3, v1
	v_lshlrev_b64 v[2:3], 0, v[2:3]
	v_lshl_add_u64 v[2:3], v[2:3], 0, s[100:101]
	v_cndmask_b32_e32 v5, v6, v7, vcc
	v_cndmask_b32_e32 v4, v8, v9, vcc
	v_lshlrev_b64 v[2:3], 7, v[2:3]
	v_lshl_add_u64 v[2:3], v[4:5], 0, v[2:3]
	v_lshl_add_u64 v[2:3], v[2:3], 0, 0
	s_movk_i32 s4, 0xf7ff
	v_lshl_add_u64 v[2:3], v[2:3], 0, v[0:1]
	v_cmp_lt_i32_e32 vcc, s4, v166
	global_load_dwordx4 v[118:121], v[2:3], off
	s_movk_i32 s4, 0x1400
	v_cndmask_b32_e32 v2, 0, v196, vcc
	v_add3_u32 v2, v166, v2, s4
	v_ashrrev_i32_e32 v2, 3, v2
	v_add_u32_e32 v2, s5, v2
	v_max_i32_e32 v2, 0, v2
	v_mov_b32_e32 v3, v1
	v_lshlrev_b64 v[2:3], 0, v[2:3]
	v_lshl_add_u64 v[2:3], v[2:3], 0, s[100:101]
	v_cndmask_b32_e32 v5, v6, v7, vcc
	v_cndmask_b32_e32 v4, v8, v9, vcc
	v_lshlrev_b64 v[2:3], 7, v[2:3]
	v_lshl_add_u64 v[2:3], v[4:5], 0, v[2:3]
	v_lshl_add_u64 v[2:3], v[2:3], 0, 0
	s_movk_i32 s4, 0xf5ff
	v_lshl_add_u64 v[2:3], v[2:3], 0, v[0:1]
	v_cmp_lt_i32_e32 vcc, s4, v166
	global_load_dwordx4 v[122:125], v[2:3], off
	s_movk_i32 s4, 0x1600
	v_cndmask_b32_e32 v2, 0, v196, vcc
	v_add3_u32 v2, v166, v2, s4
	v_ashrrev_i32_e32 v2, 3, v2
	v_add_u32_e32 v2, s5, v2
	v_max_i32_e32 v2, 0, v2
	v_mov_b32_e32 v3, v1
	v_lshlrev_b64 v[2:3], 0, v[2:3]
	v_lshl_add_u64 v[2:3], v[2:3], 0, s[100:101]
	v_cndmask_b32_e32 v5, v6, v7, vcc
	v_cndmask_b32_e32 v4, v8, v9, vcc
	v_lshlrev_b64 v[2:3], 7, v[2:3]
	v_lshl_add_u64 v[2:3], v[4:5], 0, v[2:3]
	v_lshl_add_u64 v[2:3], v[2:3], 0, 0
	v_lshl_add_u64 v[2:3], v[2:3], 0, v[0:1]
	global_load_dwordx4 v[126:129], v[2:3], off
	s_mov_b32 s4, s6
	v_writelane_b32 v250, s4, 13
	s_nop 1
	v_writelane_b32 v250, s5, 14

; __global__ void __launch_bounds__(NTHR, 2) fwd_megakernel(Args a) {
;     ...
;                         __syncthreads();
.LBB0_187:
	v_readlane_b32 s62, v249, 2
	s_waitcnt vmcnt(63) expcnt(7) lgkmcnt(15)
	s_setprio 0
	s_barrier
	s_mov_b64 s[12:13], -1
	v_readlane_b32 s63, v249, 3

; __device__ __forceinline__ unsigned xb_ld(unsigned* p)              { return __hip_atomic_load(p, __ATOMIC_RELAXED, __HIP_MEMORY_SCOPE_AGENT); }
; __device__ __forceinline__ unsigned xb_add(unsigned* p, unsigned v) { return __hip_atomic_fetch_add(p, v, __ATOMIC_RELAXED, __HIP_MEMORY_SCOPE_AGENT); }
; #define XB_SPIN(cond, bar) do { unsigned _sp = 0; while (cond) { __builtin_amdgcn_s_sleep(1); \
;     if ((++_sp & 255u) == 0u) { if (xb_ld(&(bar)[XB_TMO])) break; if (_sp > XB_SPIN_CAP) { atomicAdd(&(bar)[XB_TMO], 1u); break; } } } } while (0)
; __device__ __forceinline__ void xcd_barrier(const XcdBarrier& b) {
;     ...
;         const unsigned old = xb_add(&bar[XB_XSUB(b.x)], 1u);
;         const unsigned gen = old / nloc;
;         if (old + 1u == (gen + 1u) * nloc) {
;             __builtin_amdgcn_fence(__ATOMIC_RELEASE, "agent");
;             asm volatile("s_waitcnt vmcnt(0)" ::: "memory");
;             const unsigned og = xb_add(&bar[XB_TOP], 1u);
;             const unsigned tg = og / nx;
;             if (og + 1u == (tg + 1u) * nx) xb_add(&bar[XB_TOPGEN], 1u);
;             else XB_SPIN(xb_ld(&bar[XB_TOPGEN]) == tg, bar);
;             __builtin_amdgcn_fence(__ATOMIC_ACQUIRE, "agent");
;             xb_add(&bar[XB_XGEN(b.x)], 1u);
;             asm volatile("s_waitcnt vmcnt(0)" ::: "memory");
;         } else {
;             XB_SPIN(xb_ld(&bar[XB_XGEN(b.x)]) == gen, bar);
.LBB0_275:
	v_readlane_b32 s2, v250, 8
	s_add_u32 s26, s4, s2
	s_addc_u32 s2, s5, 0
	v_mov_b32_e32 v3, s26
	v_add_co_u32_e32 v4, vcc, 0x1000, v3
	v_mov_b32_e32 v3, s2
	s_nop 0
	v_addc_co_u32_e32 v5, vcc, 0, v3, vcc
	flat_atomic_add v3, v[4:5], v194 offset:1024 sc0
	v_cvt_f32_u32_e32 v4, v2
	v_sub_u32_e32 v5, 0, v2
	v_rcp_iflag_f32_e32 v4, v4
	s_nop 0
	v_mul_f32_e32 v4, 0x4f7ffffe, v4
	v_cvt_u32_f32_e32 v4, v4
	v_mul_lo_u32 v5, v5, v4
	v_mul_hi_u32 v5, v4, v5
	v_add_u32_e32 v4, v4, v5
	s_waitcnt vmcnt(0) lgkmcnt(0)
	buffer_inv sc1
	v_mul_hi_u32 v4, v3, v4
	v_mul_lo_u32 v5, v4, v2
	v_add_u32_e32 v6, 1, v3
	v_sub_u32_e32 v3, v3, v5
	v_add_u32_e32 v7, 1, v4
	v_sub_u32_e32 v5, v3, v2
	v_cmp_ge_u32_e32 vcc, v3, v2
	s_nop 1
	v_cndmask_b32_e32 v4, v4, v7, vcc
	v_cndmask_b32_e32 v3, v3, v5, vcc
	v_add_u32_e32 v5, 1, v4
	v_cmp_ge_u32_e32 vcc, v3, v2
	s_nop 1
	v_cndmask_b32_e32 v3, v4, v5, vcc
	v_mad_u64_u32 v[4:5], s[6:7], v2, v3, v[2:3]
	v_cmp_ne_u32_e32 vcc, v6, v4
	s_and_saveexec_b64 s[6:7], vcc
	s_xor_b64 s[6:7], exec, s[6:7]
	s_cbranch_execz .LBB0_288
	v_mov_b32_e32 v0, s26
	v_add_co_u32_e32 v4, vcc, 0x2000, v0
	v_mov_b32_e32 v0, s2
	s_nop 0
	v_addc_co_u32_e32 v5, vcc, 0, v0, vcc
	flat_load_dword v0, v[4:5] offset:1024 sc1
	s_add_u32 s10, s26, 0x2400
	s_addc_u32 s11, s2, 0
	s_waitcnt vmcnt(0) lgkmcnt(0)
	v_cmp_eq_u32_e32 vcc, v0, v3
	s_and_saveexec_b64 s[8:9], vcc
	s_cbranch_execz .LBB0_287
	s_mov_b32 s27, 1
	s_mov_b64 s[12:13], 0
	s_branch .LBB0_279

; __device__ __forceinline__ unsigned xb_ld(unsigned* p)              { return __hip_atomic_load(p, __ATOMIC_RELAXED, __HIP_MEMORY_SCOPE_AGENT); }
; __device__ __forceinline__ unsigned xb_add(unsigned* p, unsigned v) { return __hip_atomic_fetch_add(p, v, __ATOMIC_RELAXED, __HIP_MEMORY_SCOPE_AGENT); }
; #define XB_SPIN(cond, bar) do { unsigned _sp = 0; while (cond) { __builtin_amdgcn_s_sleep(1); \
;     if ((++_sp & 255u) == 0u) { if (xb_ld(&(bar)[XB_TMO])) break; if (_sp > XB_SPIN_CAP) { atomicAdd(&(bar)[XB_TMO], 1u); break; } } } } while (0)
; __device__ __forceinline__ void xcd_barrier(const XcdBarrier& b) {
;     ...
;         const unsigned old = xb_add(&bar[XB_XSUB(b.x)], 1u);
;         const unsigned gen = old / nloc;
;         if (old + 1u == (gen + 1u) * nloc) {
;             __builtin_amdgcn_fence(__ATOMIC_RELEASE, "agent");
;             asm volatile("s_waitcnt vmcnt(0)" ::: "memory");
;             const unsigned og = xb_add(&bar[XB_TOP], 1u);
;             const unsigned tg = og / nx;
;             if (og + 1u == (tg + 1u) * nx) xb_add(&bar[XB_TOPGEN], 1u);
;             else XB_SPIN(xb_ld(&bar[XB_TOPGEN]) == tg, bar);
;             __builtin_amdgcn_fence(__ATOMIC_ACQUIRE, "agent");
;             xb_add(&bar[XB_XGEN(b.x)], 1u);
;             asm volatile("s_waitcnt vmcnt(0)" ::: "memory");
;         } else {
;             XB_SPIN(xb_ld(&bar[XB_XGEN(b.x)]) == gen, bar);
;             __builtin_amdgcn_fence(__ATOMIC_ACQUIRE, "agent");
;             asm volatile("s_waitcnt vmcnt(0)" ::: "memory");
.LBB0_287:
	s_or_b64 exec, exec, s[8:9]
	s_waitcnt vmcnt(0) lgkmcnt(0)
.LBB0_288:
	s_andn2_saveexec_b64 s[6:7], s[6:7]
	s_cbranch_execz .LBB0_57
	v_mov_b32_e32 v2, s4
	v_add_co_u32_e32 v2, vcc, 0x3000, v2
	v_mov_b32_e32 v3, s5
	buffer_wbl2 sc1
	s_waitcnt vmcnt(0)
	v_addc_co_u32_e32 v3, vcc, 0, v3, vcc
	flat_atomic_add v2, v[2:3], v194 offset:1024 sc0
	v_cvt_f32_u32_e32 v3, v0
	v_sub_u32_e32 v4, 0, v0
	s_add_u32 s6, s4, 0x3500
	s_addc_u32 s7, s5, 0
	v_rcp_iflag_f32_e32 v3, v3
	s_mov_b64 s[10:11], -1
	v_mul_f32_e32 v3, 0x4f7ffffe, v3
	v_cvt_u32_f32_e32 v3, v3
	v_mul_lo_u32 v4, v4, v3
	v_mul_hi_u32 v4, v3, v4
	v_add_u32_e32 v3, v3, v4
	s_waitcnt vmcnt(0) lgkmcnt(0)
	v_mul_hi_u32 v3, v2, v3
	v_mul_lo_u32 v4, v3, v0
	v_add_u32_e32 v5, 1, v2
	v_sub_u32_e32 v2, v2, v4
	v_add_u32_e32 v6, 1, v3
	v_sub_u32_e32 v4, v2, v0
	v_cmp_ge_u32_e32 vcc, v2, v0
	s_nop 1
	v_cndmask_b32_e32 v3, v3, v6, vcc
	v_cndmask_b32_e32 v2, v2, v4, vcc
	v_add_u32_e32 v4, 1, v3
	v_cmp_ge_u32_e32 vcc, v2, v0
	s_nop 1
	v_cndmask_b32_e32 v4, v3, v4, vcc
	v_mad_u64_u32 v[2:3], s[8:9], v0, v4, v[0:1]
	v_cmp_ne_u32_e32 vcc, v5, v2
	v_mov_b64_e32 v[2:3], s[6:7]
	s_and_saveexec_b64 s[8:9], vcc
	s_cbranch_execz .LBB0_301
	v_mov_b64_e32 v[2:3], s[6:7]
	flat_load_dword v0, v[2:3] sc1
	s_mov_b64 s[14:15], 0
	s_waitcnt vmcnt(0) lgkmcnt(0)
	v_cmp_eq_u32_e32 vcc, v0, v4
	s_and_saveexec_b64 s[12:13], vcc
	s_cbranch_execz .LBB0_300
	s_add_u32 s10, s4, 0x200
	s_addc_u32 s11, s5, 0
	s_mov_b32 s24, 1
	s_mov_b64 s[4:5], 0
	s_branch .LBB0_293
